# rwkv_out: all per-unit staging loads (RHO/Y0/V, prev-V row, chunk state, gate-lora rows) and the 16 gate-weight fragment loads issued up front instead of one serialized round trip each
# speedup vs baseline: 1.0281x; 1.0083x over previous
; __device__ __forceinline__ void rwkv_out_phase(const bf16* Z, const RwkvW w, const bf16* Wl, const float* Ub, const bf16* RHO, const bf16* Y0, const float* BON, bf16* MIX, unsigned char* lds) {
;     ...
;         f32x4 ya[4], ga[4];
; #pragma unroll
;         for (int dt = 0; dt < 4; ++dt) { ya[dt] = (f32x4){0.f, 0.f, 0.f, 0.f}; ga[dt] = (f32x4){0.f, 0.f, 0.f, 0.f};
; #pragma unroll
;             for (int k0 = 0; k0 < 64; k0 += 32) ya[dt] = mma16(Rs, 72, 16 * wave, Ss, 72, 16 * dt, k0, ya[dt], lane);
;             const bf16* wg = Wl + (size_t)(1024 + col0 + 16 * dt + r16) * 256 + 128 + q4 * 8;
; #pragma unroll
;             for (int ks = 0; ks < 4; ++ks) ga[dt] = __builtin_amdgcn_mfma_f32_16x16x32_bf16(*(const bf16x8*)(AG + (16 * wave + r16) * 136 + 32 * ks + q4 * 8), *(const bf16x8*)(wg + 32 * ks), ga[dt], 0, 0, 0); }
.LBB0_641:
	s_or_b64 exec, exec, s[18:19]
	s_waitcnt lgkmcnt(0)
	s_barrier
	ds_read_b128 v[30:33], v52
	ds_read_b128 v[2:5], v102 offset:18432
	v_or_b32_e32 v69, s37, v73
	s_waitcnt lgkmcnt(0)
	v_mfma_f32_16x16x32_bf16 v[6:9], v[30:33], v[2:5], 0
	ds_read_b128 v[2:5], v52 offset:64
	ds_read_b128 v[10:13], v102 offset:18496
	v_lshlrev_b32_e32 v0, 9, v69
	v_mov_b32_e32 v67, v1
	s_waitcnt lgkmcnt(0)
	v_mfma_f32_16x16x32_bf16 v[18:21], v[2:5], v[10:13], v[6:9]
	s_mov_b64 s[18:19], 0x80100
	s_nop 1
	v_lshl_add_u64 v[6:7], s[12:13], 0, v[0:1]
	v_lshl_add_u64 v[70:71], v[6:7], 0, v[66:67]
	s_mov_b64 s[20:21], 0x80000
	v_lshl_add_u64 v[156:157], v[70:71], 0, s[20:21]
	s_mov_b64 s[20:21], 0x2000
	global_load_dwordx4 v[174:177], v[156:157], off offset:256
	global_load_dwordx4 v[178:181], v[156:157], off offset:320
	global_load_dwordx4 v[182:185], v[156:157], off offset:384
	global_load_dwordx4 v[186:189], v[156:157], off offset:448
	v_lshl_add_u64 v[156:157], v[156:157], 0, s[20:21]
	global_load_dwordx4 v[190:193], v[156:157], off offset:256
	global_load_dwordx4 v[194:197], v[156:157], off offset:320
	global_load_dwordx4 v[198:201], v[156:157], off offset:384
	global_load_dwordx4 v[202:205], v[156:157], off offset:448
	v_lshl_add_u64 v[156:157], v[156:157], 0, s[20:21]
	global_load_dwordx4 v[206:209], v[156:157], off offset:256
	global_load_dwordx4 v[210:213], v[156:157], off offset:320
	global_load_dwordx4 v[214:217], v[156:157], off offset:384
	global_load_dwordx4 v[218:221], v[156:157], off offset:448
	v_lshl_add_u64 v[156:157], v[156:157], 0, s[20:21]
	global_load_dwordx4 v[222:225], v[156:157], off offset:256
	global_load_dwordx4 v[226:229], v[156:157], off offset:320
	global_load_dwordx4 v[230:233], v[156:157], off offset:384
	global_load_dwordx4 v[114:117], v[156:157], off offset:448
	v_lshl_add_u64 v[14:15], v[70:71], 0, s[18:19]
	s_mov_b32 s18, 0x80000
	v_add_co_u32_e32 v6, vcc, s18, v70
	s_nop 0
	v_addc_co_u32_e32 v7, vcc, 0, v71, vcc
	ds_read_b128 v[38:41], v53 offset:27648
	ds_read_b128 v[34:37], v53 offset:27712
	ds_read_b128 v[42:45], v53 offset:27776
	ds_read_b128 v[46:49], v53 offset:27840
	s_mov_b64 s[18:19], 0x82100
	v_lshl_add_u64 v[26:27], v[70:71], 0, s[18:19]
	s_mov_b32 s18, 0x82000
	s_mov_b32 s20, 0x800000
	s_movk_i32 s21, 0x1000
	s_mov_b32 s25, s61
	s_waitcnt lgkmcnt(3)
	s_waitcnt vmcnt(15)
	v_mfma_f32_16x16x32_bf16 v[6:9], v[38:41], v[174:177], 0
	s_waitcnt lgkmcnt(2)
	s_waitcnt vmcnt(14)
	v_mfma_f32_16x16x32_bf16 v[6:9], v[34:37], v[178:181], v[6:9]
	s_waitcnt lgkmcnt(1)
	s_waitcnt vmcnt(13)
	v_mfma_f32_16x16x32_bf16 v[6:9], v[42:45], v[182:185], v[6:9]
	ds_read_b128 v[14:17], v102 offset:20800
	s_waitcnt lgkmcnt(1)
	s_waitcnt vmcnt(12)
	v_mfma_f32_16x16x32_bf16 v[6:9], v[46:49], v[186:189], v[6:9]
	ds_read_b128 v[10:13], v102 offset:20736
	s_waitcnt lgkmcnt(0)
	v_mfma_f32_16x16x32_bf16 v[10:13], v[30:33], v[10:13], 0
	v_mfma_f32_16x16x32_bf16 v[22:25], v[2:5], v[14:17], v[10:13]
	s_nop 5
	v_add_co_u32_e32 v10, vcc, s18, v70
	s_mov_b64 s[18:19], 0x84100
	s_nop 0
	v_addc_co_u32_e32 v11, vcc, 0, v71, vcc
	v_lshl_add_u64 v[112:113], v[70:71], 0, s[18:19]
	s_mov_b32 s18, 0x84000
	s_waitcnt vmcnt(11)
	v_mfma_f32_16x16x32_bf16 v[10:13], v[38:41], v[190:193], 0
	s_waitcnt vmcnt(10)
	v_mfma_f32_16x16x32_bf16 v[10:13], v[34:37], v[194:197], v[10:13]
	s_waitcnt vmcnt(9)
	v_mfma_f32_16x16x32_bf16 v[10:13], v[42:45], v[198:201], v[10:13]
	ds_read_b128 v[26:29], v102 offset:23104
	s_waitcnt vmcnt(8)
	v_mfma_f32_16x16x32_bf16 v[10:13], v[46:49], v[202:205], v[10:13]
	ds_read_b128 v[14:17], v102 offset:23040
	s_waitcnt lgkmcnt(0)
	v_mfma_f32_16x16x32_bf16 v[14:17], v[30:33], v[14:17], 0
	v_mfma_f32_16x16x32_bf16 v[26:29], v[2:5], v[26:29], v[14:17]
	s_nop 6
	v_add_co_u32_e32 v14, vcc, s18, v70
	s_mov_b64 s[18:19], 0x86100
	s_nop 0
	v_addc_co_u32_e32 v15, vcc, 0, v71, vcc
	s_waitcnt vmcnt(7)
	v_mfma_f32_16x16x32_bf16 v[14:17], v[38:41], v[206:209], 0
	s_waitcnt vmcnt(6)
	v_mfma_f32_16x16x32_bf16 v[14:17], v[34:37], v[210:213], v[14:17]
	s_waitcnt vmcnt(5)
	v_mfma_f32_16x16x32_bf16 v[14:17], v[42:45], v[214:217], v[14:17]
	s_waitcnt vmcnt(4)
	v_mfma_f32_16x16x32_bf16 v[14:17], v[46:49], v[218:221], v[14:17]
	ds_read_b128 v[108:111], v102 offset:25344
	s_waitcnt lgkmcnt(0)
	v_mfma_f32_16x16x32_bf16 v[30:33], v[30:33], v[108:111], 0
	ds_read_b128 v[108:111], v102 offset:25408
	s_waitcnt lgkmcnt(0)
	v_mfma_f32_16x16x32_bf16 v[30:33], v[2:5], v[108:111], v[30:33]
	v_lshl_add_u64 v[108:109], v[70:71], 0, s[18:19]
	s_mov_b32 s18, 0x86000
	v_add_co_u32_e32 v2, vcc, s18, v70
	s_lshl_b32 s18, s38, 2
	s_nop 0
	v_addc_co_u32_e32 v3, vcc, 0, v71, vcc
	s_add_u32 s18, s35, s18
	s_addc_u32 s19, s36, 0
	s_lshl_b32 s60, s37, 1
	s_add_i32 s26, s26, s70
	s_cmpk_gt_i32 s26, 0x7ff
	s_waitcnt vmcnt(3)
	v_mfma_f32_16x16x32_bf16 v[2:5], v[38:41], v[222:225], 0
	s_waitcnt vmcnt(2)
	v_mfma_f32_16x16x32_bf16 v[2:5], v[34:37], v[226:229], v[2:5]
	v_mov_b32_e32 v38, v18
	v_mov_b32_e32 v39, v22
	s_waitcnt vmcnt(1)
	v_mfma_f32_16x16x32_bf16 v[2:5], v[42:45], v[230:233], v[2:5]
	s_waitcnt vmcnt(0)
	v_mfma_f32_16x16x32_bf16 v[2:5], v[46:49], v[114:117], v[2:5]
	v_lshl_add_u64 v[34:35], s[16:17], 0, v[54:55]
	v_lshlrev_b64 v[34:35], 5, v[34:35]
	v_lshl_add_u64 v[34:35], s[18:19], 0, v[34:35]
	global_load_dword v43, v[34:35], off
	ds_read_u16 v0, v103 offset:62560
	ds_read_u16 v34, v103 offset:62528
	v_mov_b32_e32 v37, v26
	v_mov_b32_e32 v36, v30
	s_waitcnt lgkmcnt(0)
	v_lshlrev_b32_e32 v35, 16, v34
	v_lshlrev_b32_e32 v34, 16, v0
	ds_read_u16 v0, v103 offset:62464
	ds_read_u16 v26, v103 offset:62496
	v_pk_add_f32 v[34:35], v[36:37], v[34:35]
	s_waitcnt lgkmcnt(1)
; __device__ __forceinline__ float bf2f(bf16 v) { return __uint_as_float(((unsigned)v) << 16); }
; __device__ __forceinline__ unsigned f2bf(float f) { return pk2(f, f) & 0xffffu; }
; __device__ __forceinline__ float red16(float v) { v += dpp_mov<0xB1>(v); v += dpp_mov<0x4E>(v); v += dpp_mov<0x141>(v); v += dpp_mov<0x140>(v); return v; }
; __device__ __forceinline__ void rwkv_out_phase(const bf16* Z, const RwkvW w, const bf16* Wl, const float* Ub, const bf16* RHO, const bf16* Y0, const float* BON, bf16* MIX, unsigned char* lds) {
;     ...
;         for (int jj = 0; jj < 4; ++jj) { const int tl = 16 * wave + q4 * 4 + jj; const float bon = BON[(rowbase + tl) * 8 + h];
;             float y[4]; float sum = 0.f;
; #pragma unroll
;             for (int dt = 0; dt < 4; ++dt) { y[dt] = ya[dt][jj] + bf2f(Ys[tl * 72 + 16 * dt + r16]); sum += y[dt]; }
;             const float mean = red16(sum) * (1.f / 64.f); float qq = 0.f;
; #pragma unroll
;             for (int dt = 0; dt < 4; ++dt) { y[dt] -= mean; qq += y[dt] * y[dt]; }
;             const float rstd = rsqrtf(red16(qq) * (1.f / 64.f) + 64e-5f);
; #pragma unroll
;             for (int dt = 0; dt < 4; ++dt) { const int ch = 16 * dt + r16; const float vc = bf2f(Vs[(tl + 1) * 72 + ch]), vp = bf2f(Vs[tl * 72 + ch]);
;                 const float vs = vc + w.mu[1024 + col0 + ch] * (vp - vc);
;                 Ys[tl * 72 + ch] = (bf16)f2bf((y[dt] * rstd * w.ln_g[col0 + ch] + w.ln_b[col0 + ch] + bon * vs) * ga[dt][jj]); } }
	v_lshlrev_b32_e32 v36, 16, v0
	s_waitcnt lgkmcnt(0)
	v_lshlrev_b32_e32 v37, 16, v26
	v_pk_add_f32 v[36:37], v[38:39], v[36:37]
	s_nop 0
	v_add_f32_e32 v0, 0, v36
	v_add_f32_e32 v0, v0, v37
	v_add_f32_e32 v0, v0, v35
	v_add_f32_e32 v0, v0, v34
	s_nop 1
	v_add_f32_dpp v0, v0, v0 quad_perm:[1,0,3,2] row_mask:0xf bank_mask:0xf bound_ctrl:1
	s_nop 1
	v_add_f32_dpp v0, v0, v0 quad_perm:[2,3,0,1] row_mask:0xf bank_mask:0xf bound_ctrl:1
	s_nop 1
	v_add_f32_dpp v0, v0, v0 row_half_mirror row_mask:0xf bank_mask:0xf bound_ctrl:1
	s_nop 1
	v_add_f32_dpp v0, v0, v0 row_mirror row_mask:0xf bank_mask:0xf bound_ctrl:1
	v_mul_f32_e32 v0, 0x3c800000, v0
	v_pk_add_f32 v[36:37], v[36:37], v[0:1] op_sel_hi:[1,0] neg_lo:[0,1] neg_hi:[0,1]
	v_pk_add_f32 v[34:35], v[34:35], v[0:1] op_sel_hi:[1,0] neg_lo:[0,1] neg_hi:[0,1]
	v_pk_mul_f32 v[38:39], v[36:37], v[36:37]
	v_pk_mul_f32 v[40:41], v[34:35], v[34:35]
	v_add_f32_e32 v0, v38, v39
	v_add_f32_e32 v0, v41, v0
	v_add_f32_e32 v0, v40, v0
	s_nop 1
	v_add_f32_dpp v0, v0, v0 quad_perm:[1,0,3,2] row_mask:0xf bank_mask:0xf bound_ctrl:1
	s_nop 1
	v_add_f32_dpp v0, v0, v0 quad_perm:[2,3,0,1] row_mask:0xf bank_mask:0xf bound_ctrl:1
	s_nop 1
	v_add_f32_dpp v0, v0, v0 row_half_mirror row_mask:0xf bank_mask:0xf bound_ctrl:1
	s_nop 1
	v_add_f32_dpp v0, v0, v0 row_mirror row_mask:0xf bank_mask:0xf bound_ctrl:1
	v_fmamk_f32 v0, v0, 0x3c800000, v167
	v_cmp_gt_f32_e32 vcc, s20, v0
	v_mul_f32_e32 v18, 0x4b800000, v0
	s_nop 0
	v_cndmask_b32_e32 v0, v0, v18, vcc
	v_rsq_f32_e32 v0, v0
	s_nop 0
	v_mul_f32_e32 v18, 0x45800000, v0
	v_cndmask_b32_e32 v18, v0, v18, vcc
	ds_read_u16 v0, v74 offset:144
	s_waitcnt lgkmcnt(0)
	v_lshlrev_b32_e32 v22, 16, v0
	ds_read_u16 v0, v75
	s_waitcnt lgkmcnt(0)
	v_lshlrev_b32_e32 v26, 16, v0
	v_lshlrev_b32_e32 v0, 2, v69
	v_lshl_add_u64 v[38:39], s[6:7], 0, v[0:1]
	v_add_co_u32_e32 v38, vcc, s21, v38
	v_sub_f32_e32 v26, v26, v22
	s_nop 0
	v_addc_co_u32_e32 v39, vcc, 0, v39, vcc
	global_load_dword v30, v[38:39], off
	v_mov_b32_e32 v69, v1
	s_waitcnt vmcnt(0)
	v_fmac_f32_e32 v22, v30, v26
	v_mul_f32_e32 v26, v36, v18
	global_load_dword v36, v0, s[8:9]
	global_load_dword v38, v0, s[10:11]
	s_waitcnt vmcnt(0)
	v_fma_f32 v0, v36, v26, v38
	v_fmac_f32_e32 v0, v43, v22
	v_mul_f32_e32 v0, v6, v0
	v_cvt_pk_bf16_f32 v0, v0, v0
	ds_write_b16 v76, v0 offset:62464
	ds_read_u16 v0, v74 offset:176
	ds_read_u16 v6, v74 offset:208
	s_waitcnt lgkmcnt(1)
	v_lshlrev_b32_e32 v22, 16, v0
	ds_read_u16 v0, v77
	s_waitcnt lgkmcnt(1)
	v_lshlrev_b32_e32 v6, 16, v6
	s_waitcnt lgkmcnt(0)
	v_lshlrev_b32_e32 v26, 16, v0
	v_add_lshl_u32 v0, s37, v73, 2
	v_lshl_add_u64 v[40:41], s[6:7], 0, v[0:1]
	v_add_co_u32_e32 v44, vcc, s21, v40
	v_sub_f32_e32 v26, v26, v22
	s_nop 0
	v_addc_co_u32_e32 v45, vcc, 0, v41, vcc
	global_load_dword v39, v[44:45], off offset:64
	s_waitcnt vmcnt(0)
	v_fmac_f32_e32 v22, v39, v26
	v_mul_f32_e32 v26, v37, v18
	global_load_dword v37, v0, s[8:9] offset:64
	global_load_dword v40, v0, s[10:11] offset:64
	global_load_dword v41, v[44:45], off offset:128
	s_waitcnt vmcnt(1)
	v_fma_f32 v26, v37, v26, v40
	v_fmac_f32_e32 v26, v43, v22
	v_mul_f32_e32 v10, v10, v26
	v_cvt_pk_bf16_f32 v10, v10, v10
	ds_write_b16 v78, v10 offset:62496
	ds_read_u16 v10, v79
	v_mov_b32_e32 v26, v31
	v_mov_b32_e32 v22, v19
	s_waitcnt lgkmcnt(0)
	v_lshlrev_b32_e32 v10, 16, v10
	v_sub_f32_e32 v10, v10, v6
	s_waitcnt vmcnt(0)
	v_fmac_f32_e32 v6, v41, v10
	v_mul_f32_e32 v10, v35, v18
	global_load_dword v42, v0, s[8:9] offset:128
	global_load_dword v35, v0, s[10:11] offset:128
	v_mul_f32_e32 v18, v34, v18
	s_waitcnt vmcnt(0)
	v_fma_f32 v10, v42, v10, v35
	v_fmac_f32_e32 v10, v43, v6
	v_mul_f32_e32 v6, v14, v10
	v_cvt_pk_bf16_f32 v6, v6, v6
	ds_write_b16 v78, v6 offset:62528
	ds_read_u16 v6, v74 offset:240
	ds_read_u16 v10, v80
	s_waitcnt lgkmcnt(1)
	v_lshlrev_b32_e32 v6, 16, v6
	s_waitcnt lgkmcnt(0)
	v_lshlrev_b32_e32 v14, 16, v10
	global_load_dword v10, v[44:45], off offset:192
	v_sub_f32_e32 v14, v14, v6
	v_lshl_add_u64 v[44:45], s[16:17], 0, v[58:59]
	v_lshlrev_b64 v[44:45], 5, v[44:45]
	v_lshl_add_u64 v[44:45], s[18:19], 0, v[44:45]
	s_waitcnt vmcnt(0)
	v_fmac_f32_e32 v6, v10, v14
	global_load_dword v14, v0, s[8:9] offset:192
	s_nop 0
	global_load_dword v0, v0, s[10:11] offset:192
	s_waitcnt vmcnt(0)
	v_fma_f32 v18, v18, v14, v0
	v_fmac_f32_e32 v18, v43, v6
	v_mul_f32_e32 v2, v2, v18
	v_cvt_pk_bf16_f32 v2, v2, v2
	ds_write_b16 v78, v2 offset:62560
	global_load_dword v2, v[44:45], off
	ds_read_u16 v6, v103 offset:62704
	ds_read_u16 v18, v103 offset:62672
	s_waitcnt lgkmcnt(1)
	v_lshlrev_b32_e32 v44, 16, v6
	s_waitcnt lgkmcnt(0)
	v_lshlrev_b32_e32 v45, 16, v18
	ds_read_u16 v6, v103 offset:62608
	ds_read_u16 v18, v103 offset:62640
	v_pk_add_f32 v[26:27], v[26:27], v[44:45]
	s_waitcnt lgkmcnt(1)
	v_lshlrev_b32_e32 v44, 16, v6
	s_waitcnt lgkmcnt(0)
	v_lshlrev_b32_e32 v45, 16, v18
	v_pk_add_f32 v[18:19], v[22:23], v[44:45]
	s_nop 0
	v_add_f32_e32 v6, 0, v18
	v_add_f32_e32 v6, v6, v19
	v_add_f32_e32 v6, v6, v27
	v_add_f32_e32 v6, v6, v26
	s_nop 1
	v_add_f32_dpp v6, v6, v6 quad_perm:[1,0,3,2] row_mask:0xf bank_mask:0xf bound_ctrl:1
	s_nop 1
	v_add_f32_dpp v6, v6, v6 quad_perm:[2,3,0,1] row_mask:0xf bank_mask:0xf bound_ctrl:1
	s_nop 1
	v_add_f32_dpp v6, v6, v6 row_half_mirror row_mask:0xf bank_mask:0xf bound_ctrl:1
	s_nop 1
	v_add_f32_dpp v6, v6, v6 row_mirror row_mask:0xf bank_mask:0xf bound_ctrl:1
	v_mul_f32_e32 v6, 0x3c800000, v6
	v_pk_add_f32 v[22:23], v[18:19], v[6:7] op_sel_hi:[1,0] neg_lo:[0,1] neg_hi:[0,1]
	v_pk_add_f32 v[18:19], v[26:27], v[6:7] op_sel_hi:[1,0] neg_lo:[0,1] neg_hi:[0,1]
	v_pk_mul_f32 v[44:45], v[22:23], v[22:23]
	v_pk_mul_f32 v[26:27], v[18:19], v[18:19]
	v_add_f32_e32 v6, v44, v45
	v_add_f32_e32 v6, v27, v6
	v_add_f32_e32 v6, v26, v6
	ds_read_u16 v27, v82
	s_waitcnt lgkmcnt(0)
; __device__ __forceinline__ float bf2f(bf16 v) { return __uint_as_float(((unsigned)v) << 16); }
; __device__ __forceinline__ unsigned f2bf(float f) { return pk2(f, f) & 0xffffu; }
; __device__ __forceinline__ float red16(float v) { v += dpp_mov<0xB1>(v); v += dpp_mov<0x4E>(v); v += dpp_mov<0x141>(v); v += dpp_mov<0x140>(v); return v; }
; __device__ __forceinline__ void rwkv_out_phase(const bf16* Z, const RwkvW w, const bf16* Wl, const float* Ub, const bf16* RHO, const bf16* Y0, const float* BON, bf16* MIX, unsigned char* lds) {
;     ...
;         for (int jj = 0; jj < 4; ++jj) { const int tl = 16 * wave + q4 * 4 + jj; const float bon = BON[(rowbase + tl) * 8 + h];
;             float y[4]; float sum = 0.f;
; #pragma unroll
;             for (int dt = 0; dt < 4; ++dt) { y[dt] = ya[dt][jj] + bf2f(Ys[tl * 72 + 16 * dt + r16]); sum += y[dt]; }
;             const float mean = red16(sum) * (1.f / 64.f); float qq = 0.f;
; #pragma unroll
;             for (int dt = 0; dt < 4; ++dt) { y[dt] -= mean; qq += y[dt] * y[dt]; }
;             const float rstd = rsqrtf(red16(qq) * (1.f / 64.f) + 64e-5f);
; #pragma unroll
;             for (int dt = 0; dt < 4; ++dt) { const int ch = 16 * dt + r16; const float vc = bf2f(Vs[(tl + 1) * 72 + ch]), vp = bf2f(Vs[tl * 72 + ch]);
;                 const float vs = vc + w.mu[1024 + col0 + ch] * (vp - vc);
;                 Ys[tl * 72 + ch] = (bf16)f2bf((y[dt] * rstd * w.ln_g[col0 + ch] + w.ln_b[col0 + ch] + bon * vs) * ga[dt][jj]); } }
	v_lshlrev_b32_e32 v27, 16, v27
	v_add_f32_dpp v6, v6, v6 quad_perm:[1,0,3,2] row_mask:0xf bank_mask:0xf bound_ctrl:1
	s_nop 1
	v_add_f32_dpp v6, v6, v6 quad_perm:[2,3,0,1] row_mask:0xf bank_mask:0xf bound_ctrl:1
	s_nop 1
	v_add_f32_dpp v6, v6, v6 row_half_mirror row_mask:0xf bank_mask:0xf bound_ctrl:1
	s_nop 1
	v_add_f32_dpp v6, v6, v6 row_mirror row_mask:0xf bank_mask:0xf bound_ctrl:1
	v_fmamk_f32 v6, v6, 0x3c800000, v167
	v_cmp_gt_f32_e32 vcc, s20, v6
	v_mul_f32_e32 v26, 0x4b800000, v6
	s_nop 0
	v_cndmask_b32_e32 v6, v6, v26, vcc
	v_rsq_f32_e32 v6, v6
	s_nop 0
	v_mul_f32_e32 v26, 0x45800000, v6
	v_cndmask_b32_e32 v6, v6, v26, vcc
	ds_read_u16 v26, v81 offset:144
	v_mul_f32_e32 v22, v22, v6
	v_fma_f32 v22, v36, v22, v38
	s_waitcnt lgkmcnt(0)
	v_lshlrev_b32_e32 v26, 16, v26
	v_sub_f32_e32 v27, v27, v26
	v_fmac_f32_e32 v26, v30, v27
	s_waitcnt vmcnt(0)
	v_fmac_f32_e32 v22, v2, v26
	v_mul_f32_e32 v7, v7, v22
	v_cvt_pk_bf16_f32 v7, v7, v7
	ds_write_b16 v83, v7 offset:62464
	ds_read_u16 v7, v81 offset:176
	ds_read_u16 v22, v84
	s_waitcnt lgkmcnt(1)
	v_lshlrev_b32_e32 v7, 16, v7
	s_waitcnt lgkmcnt(0)
	v_lshlrev_b32_e32 v22, 16, v22
	v_sub_f32_e32 v22, v22, v7
	v_fmac_f32_e32 v7, v39, v22
	v_mul_f32_e32 v22, v23, v6
	v_fma_f32 v22, v37, v22, v40
	v_fmac_f32_e32 v22, v2, v7
	v_mul_f32_e32 v7, v11, v22
	v_cvt_pk_bf16_f32 v7, v7, v7
	ds_write_b16 v83, v7 offset:62496
	ds_read_u16 v7, v81 offset:208
	ds_read_u16 v11, v85
	s_waitcnt lgkmcnt(1)
	v_lshlrev_b32_e32 v7, 16, v7
	s_waitcnt lgkmcnt(0)
	v_lshlrev_b32_e32 v11, 16, v11
	v_sub_f32_e32 v11, v11, v7
	v_fmac_f32_e32 v7, v41, v11
	v_mul_f32_e32 v11, v19, v6
	v_fma_f32 v11, v42, v11, v35
	v_fmac_f32_e32 v11, v2, v7
	v_mul_f32_e32 v7, v15, v11
	v_cvt_pk_bf16_f32 v7, v7, v7
	ds_write_b16 v83, v7 offset:62528
	ds_read_u16 v7, v81 offset:240
	ds_read_u16 v11, v86
	v_mul_f32_e32 v6, v18, v6
	v_fma_f32 v6, v14, v6, v0
	v_mov_b32_e32 v18, v20
	s_waitcnt lgkmcnt(1)
	v_lshlrev_b32_e32 v7, 16, v7
	s_waitcnt lgkmcnt(0)
	v_lshlrev_b32_e32 v11, 16, v11
	v_sub_f32_e32 v11, v11, v7
	v_fmac_f32_e32 v7, v10, v11
	v_fmac_f32_e32 v6, v2, v7
	v_mul_f32_e32 v2, v3, v6
	v_cvt_pk_bf16_f32 v2, v2, v2
	ds_write_b16 v83, v2 offset:62560
	v_lshl_add_u64 v[2:3], s[16:17], 0, v[60:61]
	v_lshlrev_b64 v[2:3], 5, v[2:3]
	v_lshl_add_u64 v[2:3], s[18:19], 0, v[2:3]
	global_load_dword v11, v[2:3], off
	ds_read_u16 v2, v104 offset:62560
	ds_read_u16 v3, v104 offset:62528
	v_mov_b32_e32 v6, v32
	v_mov_b32_e32 v7, v28
	v_mov_b32_e32 v19, v24
	s_waitcnt lgkmcnt(1)
	v_lshlrev_b32_e32 v2, 16, v2
	s_waitcnt lgkmcnt(0)
	v_lshlrev_b32_e32 v3, 16, v3
	v_pk_add_f32 v[2:3], v[6:7], v[2:3]
	ds_read_u16 v6, v104 offset:62464
	ds_read_u16 v7, v104 offset:62496
	v_mov_b32_e32 v24, v21
	v_mov_b32_e32 v28, v33
	s_waitcnt lgkmcnt(1)
	v_lshlrev_b32_e32 v6, 16, v6
	s_waitcnt lgkmcnt(0)
	v_lshlrev_b32_e32 v7, 16, v7
	v_pk_add_f32 v[6:7], v[18:19], v[6:7]
	s_nop 0
	v_add_f32_e32 v15, 0, v6
	v_add_f32_e32 v15, v15, v7
	v_add_f32_e32 v15, v15, v3
	v_add_f32_e32 v15, v15, v2
	s_nop 1
	v_add_f32_dpp v15, v15, v15 quad_perm:[1,0,3,2] row_mask:0xf bank_mask:0xf bound_ctrl:1
	s_nop 1
	v_add_f32_dpp v15, v15, v15 quad_perm:[2,3,0,1] row_mask:0xf bank_mask:0xf bound_ctrl:1
	s_nop 1
	v_add_f32_dpp v15, v15, v15 row_half_mirror row_mask:0xf bank_mask:0xf bound_ctrl:1
	s_nop 1
	v_add_f32_dpp v15, v15, v15 row_mirror row_mask:0xf bank_mask:0xf bound_ctrl:1
	v_mul_f32_e32 v18, 0x3c800000, v15
	v_pk_add_f32 v[6:7], v[6:7], v[18:19] op_sel_hi:[1,0] neg_lo:[0,1] neg_hi:[0,1]
	v_pk_add_f32 v[2:3], v[2:3], v[18:19] op_sel_hi:[1,0] neg_lo:[0,1] neg_hi:[0,1]
	v_pk_mul_f32 v[22:23], v[6:7], v[6:7]
	v_pk_mul_f32 v[18:19], v[2:3], v[2:3]
	v_add_f32_e32 v15, v22, v23
	v_add_f32_e32 v15, v19, v15
	v_add_f32_e32 v15, v18, v15
	ds_read_u16 v19, v88
	s_waitcnt lgkmcnt(0)
	v_lshlrev_b32_e32 v19, 16, v19
	v_add_f32_dpp v15, v15, v15 quad_perm:[1,0,3,2] row_mask:0xf bank_mask:0xf bound_ctrl:1
	s_nop 1
	v_add_f32_dpp v15, v15, v15 quad_perm:[2,3,0,1] row_mask:0xf bank_mask:0xf bound_ctrl:1
	s_nop 1
	v_add_f32_dpp v15, v15, v15 row_half_mirror row_mask:0xf bank_mask:0xf bound_ctrl:1
	s_nop 1
	v_add_f32_dpp v15, v15, v15 row_mirror row_mask:0xf bank_mask:0xf bound_ctrl:1
	v_fmamk_f32 v15, v15, 0x3c800000, v167
	v_cmp_gt_f32_e32 vcc, s20, v15
	v_mul_f32_e32 v18, 0x4b800000, v15
	s_nop 0
	v_cndmask_b32_e32 v15, v15, v18, vcc
	v_rsq_f32_e32 v15, v15
	s_nop 0
	v_mul_f32_e32 v18, 0x45800000, v15
	v_cndmask_b32_e32 v15, v15, v18, vcc
	ds_read_u16 v18, v87 offset:144
	v_mul_f32_e32 v6, v6, v15
	v_fma_f32 v6, v36, v6, v38
	v_mul_f32_e32 v7, v7, v15
	v_fma_f32 v7, v37, v7, v40
	s_waitcnt lgkmcnt(0)
	v_lshlrev_b32_e32 v18, 16, v18
	v_sub_f32_e32 v19, v19, v18
	v_fmac_f32_e32 v18, v30, v19
	v_mul_f32_e32 v3, v3, v15
	v_fma_f32 v3, v42, v3, v35
	v_mul_f32_e32 v2, v2, v15
	v_fma_f32 v2, v14, v2, v0
	s_waitcnt vmcnt(0)
	v_fmac_f32_e32 v6, v11, v18
	v_mul_f32_e32 v6, v8, v6
	v_cvt_pk_bf16_f32 v6, v6, v6
	ds_write_b16 v89, v6 offset:62464
	ds_read_u16 v6, v87 offset:176
	ds_read_u16 v8, v87 offset:208
	ds_read_u16 v18, v90
	s_waitcnt lgkmcnt(2)
; __device__ __forceinline__ float bf2f(bf16 v) { return __uint_as_float(((unsigned)v) << 16); }
; __device__ __forceinline__ unsigned f2bf(float f) { return pk2(f, f) & 0xffffu; }
; __device__ __forceinline__ float red16(float v) { v += dpp_mov<0xB1>(v); v += dpp_mov<0x4E>(v); v += dpp_mov<0x141>(v); v += dpp_mov<0x140>(v); return v; }
; __device__ __forceinline__ void rwkv_out_phase(const bf16* Z, const RwkvW w, const bf16* Wl, const float* Ub, const bf16* RHO, const bf16* Y0, const float* BON, bf16* MIX, unsigned char* lds) {
;     ...
;         for (int jj = 0; jj < 4; ++jj) { const int tl = 16 * wave + q4 * 4 + jj; const float bon = BON[(rowbase + tl) * 8 + h];
;             float y[4]; float sum = 0.f;
; #pragma unroll
;             for (int dt = 0; dt < 4; ++dt) { y[dt] = ya[dt][jj] + bf2f(Ys[tl * 72 + 16 * dt + r16]); sum += y[dt]; }
;             const float mean = red16(sum) * (1.f / 64.f); float qq = 0.f;
; #pragma unroll
;             for (int dt = 0; dt < 4; ++dt) { y[dt] -= mean; qq += y[dt] * y[dt]; }
;             const float rstd = rsqrtf(red16(qq) * (1.f / 64.f) + 64e-5f);
; #pragma unroll
;             for (int dt = 0; dt < 4; ++dt) { const int ch = 16 * dt + r16; const float vc = bf2f(Vs[(tl + 1) * 72 + ch]), vp = bf2f(Vs[tl * 72 + ch]);
;                 const float vs = vc + w.mu[1024 + col0 + ch] * (vp - vc);
;                 Ys[tl * 72 + ch] = (bf16)f2bf((y[dt] * rstd * w.ln_g[col0 + ch] + w.ln_b[col0 + ch] + bon * vs) * ga[dt][jj]); } }
; #pragma unroll
;         for (int t2 = 0; t2 < 2; ++t2) { const int cidx = lane + 64 * t2, i = 16 * wave + (cidx >> 3), c8 = (cidx & 7) * 8;
;             *(u32x4*)(MIX + (rowbase + i) * DM + 512 + col0 + c8) = *(const u32x4*)(Ys + i * 72 + c8); }
	v_lshlrev_b32_e32 v6, 16, v6
	s_waitcnt lgkmcnt(0)
	v_lshlrev_b32_e32 v18, 16, v18
	v_sub_f32_e32 v18, v18, v6
	v_fmac_f32_e32 v6, v39, v18
	v_fmac_f32_e32 v7, v11, v6
	v_mul_f32_e32 v6, v12, v7
	v_cvt_pk_bf16_f32 v6, v6, v6
	ds_write_b16 v91, v6 offset:62496
	ds_read_u16 v7, v92
	v_lshlrev_b32_e32 v6, 16, v8
	s_waitcnt lgkmcnt(0)
	v_lshlrev_b32_e32 v7, 16, v7
	v_sub_f32_e32 v7, v7, v6
	v_fmac_f32_e32 v6, v41, v7
	v_fmac_f32_e32 v3, v11, v6
	v_mul_f32_e32 v3, v16, v3
	v_cvt_pk_bf16_f32 v3, v3, v3
	ds_write_b16 v91, v3 offset:62528
	ds_read_u16 v3, v87 offset:240
	ds_read_u16 v6, v93
	s_waitcnt lgkmcnt(1)
	v_lshlrev_b32_e32 v3, 16, v3
	s_waitcnt lgkmcnt(0)
	v_lshlrev_b32_e32 v6, 16, v6
	v_sub_f32_e32 v6, v6, v3
	v_fmac_f32_e32 v3, v10, v6
	v_fmac_f32_e32 v2, v11, v3
	v_mul_f32_e32 v2, v4, v2
	v_cvt_pk_bf16_f32 v2, v2, v2
	ds_write_b16 v91, v2 offset:62560
	v_lshl_add_u64 v[2:3], s[16:17], 0, v[62:63]
	v_lshlrev_b64 v[2:3], 5, v[2:3]
	v_lshl_add_u64 v[2:3], s[18:19], 0, v[2:3]
	global_load_dword v4, v[2:3], off
	ds_read_u16 v2, v104 offset:62704
	ds_read_u16 v3, v104 offset:62672
	ds_read_u16 v6, v104 offset:62608
	ds_read_u16 v7, v104 offset:62640
	ds_read_u16 v12, v95
	s_waitcnt lgkmcnt(4)
	v_lshlrev_b32_e32 v2, 16, v2
	s_waitcnt lgkmcnt(2)
	v_lshlrev_b32_e32 v6, 16, v6
	s_waitcnt lgkmcnt(1)
	v_lshlrev_b32_e32 v7, 16, v7
	v_pk_add_f32 v[6:7], v[24:25], v[6:7]
	v_lshlrev_b32_e32 v3, 16, v3
	v_add_f32_e32 v8, 0, v6
	v_pk_add_f32 v[2:3], v[28:29], v[2:3]
	v_add_f32_e32 v8, v8, v7
	v_add_f32_e32 v8, v8, v3
	v_add_f32_e32 v8, v8, v2
	s_waitcnt lgkmcnt(0)
	v_lshlrev_b32_e32 v12, 16, v12
	v_add_f32_dpp v8, v8, v8 quad_perm:[1,0,3,2] row_mask:0xf bank_mask:0xf bound_ctrl:1
	s_nop 1
	v_add_f32_dpp v8, v8, v8 quad_perm:[2,3,0,1] row_mask:0xf bank_mask:0xf bound_ctrl:1
	s_nop 1
	v_add_f32_dpp v8, v8, v8 row_half_mirror row_mask:0xf bank_mask:0xf bound_ctrl:1
	s_nop 1
	v_add_f32_dpp v8, v8, v8 row_mirror row_mask:0xf bank_mask:0xf bound_ctrl:1
	v_mul_f32_e32 v8, 0x3c800000, v8
	v_pk_add_f32 v[6:7], v[6:7], v[8:9] op_sel_hi:[1,0] neg_lo:[0,1] neg_hi:[0,1]
	v_pk_add_f32 v[2:3], v[2:3], v[8:9] op_sel_hi:[1,0] neg_lo:[0,1] neg_hi:[0,1]
	v_pk_mul_f32 v[18:19], v[6:7], v[6:7]
	v_pk_mul_f32 v[20:21], v[2:3], v[2:3]
	v_add_f32_e32 v8, v18, v19
	v_add_f32_e32 v8, v21, v8
	v_add_f32_e32 v8, v20, v8
	s_nop 1
	v_add_f32_dpp v8, v8, v8 quad_perm:[1,0,3,2] row_mask:0xf bank_mask:0xf bound_ctrl:1
	s_nop 1
	v_add_f32_dpp v8, v8, v8 quad_perm:[2,3,0,1] row_mask:0xf bank_mask:0xf bound_ctrl:1
	s_nop 1
	v_add_f32_dpp v8, v8, v8 row_half_mirror row_mask:0xf bank_mask:0xf bound_ctrl:1
	s_nop 1
	v_add_f32_dpp v8, v8, v8 row_mirror row_mask:0xf bank_mask:0xf bound_ctrl:1
	v_fmamk_f32 v8, v8, 0x3c800000, v167
	v_cmp_gt_f32_e32 vcc, s20, v8
	v_mul_f32_e32 v11, 0x4b800000, v8
	s_nop 0
	v_cndmask_b32_e32 v8, v8, v11, vcc
	v_rsq_f32_e32 v8, v8
	s_nop 0
	v_mul_f32_e32 v11, 0x45800000, v8
	v_cndmask_b32_e32 v8, v8, v11, vcc
	ds_read_u16 v11, v94 offset:144
	v_mul_f32_e32 v6, v6, v8
	v_fmac_f32_e32 v38, v36, v6
	v_mul_f32_e32 v7, v7, v8
	v_fmac_f32_e32 v40, v37, v7
	s_waitcnt lgkmcnt(0)
	v_lshlrev_b32_e32 v11, 16, v11
	v_sub_f32_e32 v12, v12, v11
	v_fmac_f32_e32 v11, v30, v12
	v_mul_f32_e32 v3, v3, v8
	v_fmac_f32_e32 v35, v42, v3
	v_mul_f32_e32 v2, v2, v8
	v_fmac_f32_e32 v0, v14, v2
	s_waitcnt vmcnt(0)
	v_fmac_f32_e32 v38, v4, v11
	v_mul_f32_e32 v6, v9, v38
	v_cvt_pk_bf16_f32 v6, v6, v6
	ds_write_b16 v96, v6 offset:62464
	ds_read_u16 v6, v94 offset:176
	ds_read_u16 v9, v97
	s_waitcnt lgkmcnt(1)
	v_lshlrev_b32_e32 v6, 16, v6
	s_waitcnt lgkmcnt(0)
	v_lshlrev_b32_e32 v9, 16, v9
	v_sub_f32_e32 v9, v9, v6
	v_fmac_f32_e32 v6, v39, v9
	v_fmac_f32_e32 v40, v4, v6
	v_mul_f32_e32 v6, v13, v40
	v_cvt_pk_bf16_f32 v6, v6, v6
	ds_write_b16 v96, v6 offset:62496
	ds_read_u16 v6, v94 offset:208
	ds_read_u16 v7, v98
	s_waitcnt lgkmcnt(1)
	v_lshlrev_b32_e32 v6, 16, v6
	s_waitcnt lgkmcnt(0)
	v_lshlrev_b32_e32 v7, 16, v7
	v_sub_f32_e32 v7, v7, v6
	v_fmac_f32_e32 v6, v41, v7
	v_fmac_f32_e32 v35, v4, v6
	v_mul_f32_e32 v3, v17, v35
	v_cvt_pk_bf16_f32 v3, v3, v3
	ds_write_b16 v96, v3 offset:62528
	ds_read_u16 v3, v94 offset:240
	ds_read_u16 v6, v99
	s_waitcnt lgkmcnt(1)
	v_lshlrev_b32_e32 v3, 16, v3
	s_waitcnt lgkmcnt(0)
	v_lshlrev_b32_e32 v6, 16, v6
	v_sub_f32_e32 v6, v6, v3
	v_fmac_f32_e32 v3, v10, v6
	v_fmac_f32_e32 v0, v4, v3
	v_mul_f32_e32 v0, v5, v0
	v_cvt_pk_bf16_f32 v0, v0, v0
	ds_write_b16 v96, v0 offset:62560
	ds_read_b128 v[2:5], v105 offset:62464
	v_lshl_add_u64 v[6:7], s[16:17], 0, v[56:57]
	v_lshlrev_b64 v[6:7], 11, v[6:7]
	v_lshl_add_u64 v[6:7], s[58:59], 0, v[6:7]
	v_lshl_add_u64 v[6:7], v[6:7], 0, s[60:61]
	v_lshl_add_u64 v[6:7], v[6:7], 0, v[68:69]
	s_waitcnt lgkmcnt(0)
	global_store_dwordx4 v[6:7], v[2:5], off offset:1024
	ds_read_b128 v[2:5], v106 offset:62464
	v_lshl_add_u64 v[6:7], s[16:17], 0, v[64:65]
	v_lshlrev_b64 v[6:7], 11, v[6:7]
	v_lshl_add_u64 v[6:7], s[58:59], 0, v[6:7]
	v_lshl_add_u64 v[6:7], v[6:7], 0, s[60:61]
	v_lshl_add_u64 v[6:7], v[6:7], 0, v[68:69]
	s_waitcnt lgkmcnt(0)
	global_store_dwordx4 v[6:7], v[2:5], off offset:1024
	s_cbranch_scc1 .LBB0_660

; __device__ __forceinline__ unsigned pk2(float lo, float hi) { unsigned r; asm("v_cvt_pk_bf16_f32 %0, %1, %2" : "=v"(r) : "v"(lo), "v"(hi)); return r; }
; __device__ __forceinline__ void rwkv_out_phase(const bf16* Z, const RwkvW w, const bf16* Wl, const float* Ub, const bf16* RHO, const bf16* Y0, const float* BON, bf16* MIX, unsigned char* lds) {
;     ...
;         if (tid < 8) { u32x4 pv = {0u, 0u, 0u, 0u}; if (c > 0) pv = *(const u32x4*)(Z + (rowbase - 1) * EVEN_IN + 3072 + col0 + tid * 8); *(u32x4*)(Vs + tid * 8) = pv; }
;         for (int i4 = tid; i4 < 1024; i4 += NTHR) { const int i = i4 >> 4, k4 = (i4 & 15) * 4; f32x4 sv = {0.f, 0.f, 0.f, 0.f};
;             if ((c >> SLOG) > 0) sv = *(const f32x4*)(Ub + (size_t)(bh * NCHK + (c >> SLOG) - 1) * 4096 + i * 64 + k4);
;             *(u32x2*)(Ss + i * 72 + k4) = (u32x2){pk2(sv[0], sv[1]), pk2(sv[2], sv[3])}; }
.LBB0_645:
	s_movk_i32 s41, 0x1ff
	s_or_b64 exec, exec, s[18:19]
	v_mov_b32_e32 v118, 0
	v_mov_b32_e32 v119, 0
	v_mov_b32_e32 v120, 0
	v_mov_b32_e32 v121, 0
	s_cmp_eq_u32 s39, 0
	s_cbranch_scc1 .Lrw_b_skip
	s_mul_i32 s20, s17, 0x1e00
	s_mul_hi_u32 s21, s16, 0x1e00
	s_add_i32 s21, s21, s20
	s_mul_i32 s20, s16, 0x1e00
	s_add_u32 s20, s94, s20
	s_addc_u32 s21, s95, s21
	s_lshl_b32 s22, s37, 1
	s_add_u32 s20, s20, s22
	s_addc_u32 s21, s21, 0
	s_and_saveexec_b64 s[18:19], s[2:3]
	v_lshl_add_u64 v[2:3], v[50:51], 1, s[20:21]
	global_load_dwordx4 v[118:121], v[2:3], off offset:-1536
	s_or_b64 exec, exec, s[18:19]
.Lrw_b_skip:
	s_mov_b32 s42, 0x10000
	s_mov_b32 s43, 0x14000
	s_cmp_gt_u32 s39, 7
	s_cselect_b64 s[20:21], -1, 0
	s_lshr_b32 s22, s39, 3
	s_lshl_b32 s23, s40, 4
	s_or_b32 s22, s22, s23
	s_add_i32 s22, s22, -1
	s_ashr_i32 s23, s22, 31
	s_lshl_b64 s[22:23], s[22:23], 14
	s_add_u32 s22, s27, s22
	s_addc_u32 s23, s28, s23
	v_ashrrev_i32_e32 v8, 4, v72
	v_and_b32_e32 v9, 60, v100
	v_mov_b32_e32 v2, 0
	v_mov_b32_e32 v3, 0
	v_mov_b32_e32 v4, 0
	v_mov_b32_e32 v5, 0
	v_mov_b32_e32 v114, 0
	v_mov_b32_e32 v115, 0
	v_mov_b32_e32 v116, 0
	v_mov_b32_e32 v117, 0
	s_and_b64 vcc, exec, s[20:21]
	s_cbranch_vccz .Lrw_c_nost
	v_lshlrev_b32_e32 v10, 6, v8
	v_ashrrev_i32_e32 v11, 31, v10
	v_lshl_add_u64 v[10:11], v[10:11], 2, s[22:23]
	v_lshlrev_b32_e32 v0, 2, v9
	s_mov_b64 s[24:25], 0x2000
	v_lshl_add_u64 v[10:11], v[10:11], 0, v[0:1]
	global_load_dwordx4 v[2:5], v[10:11], off
	v_lshl_add_u64 v[12:13], v[10:11], 0, s[24:25]
	global_load_dwordx4 v[114:117], v[12:13], off
.Lrw_c_nost:
	v_mul_lo_u32 v0, v8, s64
	v_lshlrev_b32_e32 v6, 1, v9
	v_add3_u32 v0, 0, v0, v6
	s_waitcnt vmcnt(0)
	s_and_saveexec_b64 s[18:19], s[2:3]
	ds_write_b128 v101, v[118:121]
	s_or_b64 exec, exec, s[18:19]
	v_cvt_pk_bf16_f32 v2, v2, v3
	v_cvt_pk_bf16_f32 v3, v4, v5
	v_cvt_pk_bf16_f32 v114, v114, v115
	v_cvt_pk_bf16_f32 v115, v116, v117
	ds_write_b64 v0, v[2:3] offset:18432
	ds_write_b64 v0, v[114:115] offset:23040
	s_mov_b64 s[24:25], 0
